# grid barrier: non-leader workgroups poll the top release generation directly (skip per-XCD relay hop)
# baseline (speedup 1.0000x reference)
.LBB0_234:
	s_or_b64 exec, exec, s[4:5]
	v_cvt_f32_u32_e32 v4, v2
	s_waitcnt vmcnt(0)
	v_readfirstlane_b32 s4, v3
	v_sub_u32_e32 v3, 0, v2
	v_rcp_iflag_f32_e32 v4, v4
	v_add_u32_e32 v5, s4, v1
	v_mul_f32_e32 v4, 0x4f7ffffe, v4
	v_cvt_u32_f32_e32 v4, v4
	v_mul_lo_u32 v1, v3, v4
	v_mul_hi_u32 v1, v4, v1
	v_add_u32_e32 v1, v4, v1
	v_mul_hi_u32 v1, v5, v1
	v_mul_lo_u32 v3, v1, v2
	v_sub_u32_e32 v3, v5, v3
	v_add_u32_e32 v4, 1, v1
	v_cmp_ge_u32_e32 vcc, v3, v2
	s_nop 1
	v_cndmask_b32_e32 v1, v1, v4, vcc
	v_sub_u32_e32 v4, v3, v2
	v_cndmask_b32_e32 v3, v3, v4, vcc
	v_add_u32_e32 v4, 1, v1
	v_cmp_ge_u32_e32 vcc, v3, v2
	v_add_u32_e32 v3, 1, v5
	s_nop 0
	v_cndmask_b32_e32 v1, v1, v4, vcc
	v_mul_lo_u32 v4, v2, v1
	v_add_u32_e32 v2, v4, v2
	v_cmp_ne_u32_e32 vcc, v3, v2
	s_and_saveexec_b64 s[4:5], vcc
	s_xor_b64 s[4:5], exec, s[4:5]
	s_cbranch_execz .LBB0_248
	v_readlane_b32 s6, v236, 10
	v_readlane_b32 s7, v236, 11
	s_waitcnt lgkmcnt(0)
	s_nop 3
	global_load_dword v0, v81, s[6:7] sc1
	s_waitcnt vmcnt(0)
	v_cmp_eq_u32_e32 vcc, v0, v1
	s_and_saveexec_b64 s[6:7], vcc
	s_cbranch_execz .LBB0_247
	s_mov_b32 s33, 1
	s_mov_b64 s[8:9], 0
	s_branch .LBB0_238

.LBB0_240:
	v_readlane_b32 s38, v236, 10
	v_readlane_b32 s39, v236, 11
	s_add_i32 s33, s33, 1
	s_mov_b64 s[40:41], -1
	s_nop 2
	global_load_dword v0, v81, s[38:39] sc1
	s_waitcnt vmcnt(0)
	v_cmp_ne_u32_e32 vcc, v0, v1
	s_orn2_b64 s[38:39], vcc, exec
	s_branch .LBB0_237
